# ssd_states dt projection: 32 loads per iteration issued up front into distinct quads with counted vmcnt (was one vmcnt(0) round trip per MFMA)
# baseline (speedup 1.0000x reference)
.LBB0_754:
	v_lshl_add_u64 v[10:11], v[0:1], 0, s[2:3]
	v_add_co_u32_e32 v10, vcc, 0x3610000, v10
	v_lshl_add_u64 v[12:13], v[8:9], 0, s[2:3]
	s_nop 0
	v_addc_co_u32_e32 v11, vcc, 0, v11, vcc
	global_load_dwordx4 v[16:19], v[10:11], off offset:1024
	global_load_dwordx4 v[84:87], v[12:13], off offset:-512
	global_load_dwordx4 v[20:23], v[10:11], off offset:1088
	global_load_dwordx4 v[88:91], v[12:13], off offset:-448
	global_load_dwordx4 v[24:27], v[10:11], off offset:1152
	global_load_dwordx4 v[92:95], v[12:13], off offset:-384
	global_load_dwordx4 v[28:31], v[10:11], off offset:1216
	global_load_dwordx4 v[96:99], v[12:13], off offset:-320
	global_load_dwordx4 v[32:35], v[10:11], off offset:1280
	global_load_dwordx4 v[100:103], v[12:13], off offset:-256
	global_load_dwordx4 v[36:39], v[10:11], off offset:1344
	global_load_dwordx4 v[104:107], v[12:13], off offset:-192
	global_load_dwordx4 v[40:43], v[10:11], off offset:1408
	global_load_dwordx4 v[108:111], v[12:13], off offset:-128
	global_load_dwordx4 v[44:47], v[10:11], off offset:1472
	global_load_dwordx4 v[112:115], v[12:13], off offset:-64
	global_load_dwordx4 v[48:51], v[10:11], off offset:1536
	global_load_dwordx4 v[116:119], v[12:13], off
	global_load_dwordx4 v[52:55], v[10:11], off offset:1600
	global_load_dwordx4 v[120:123], v[12:13], off offset:64
	global_load_dwordx4 v[56:59], v[10:11], off offset:1664
	global_load_dwordx4 v[124:127], v[12:13], off offset:128
	global_load_dwordx4 v[60:63], v[10:11], off offset:1728
	global_load_dwordx4 v[140:143], v[12:13], off offset:192
	global_load_dwordx4 v[68:71], v[10:11], off offset:1792
	global_load_dwordx4 v[144:147], v[12:13], off offset:256
	global_load_dwordx4 v[72:75], v[10:11], off offset:1856
	global_load_dwordx4 v[148:151], v[12:13], off offset:320
	global_load_dwordx4 v[76:79], v[10:11], off offset:1920
	global_load_dwordx4 v[152:155], v[12:13], off offset:384
	global_load_dwordx4 v[80:83], v[10:11], off offset:1984
	global_load_dwordx4 v[160:163], v[12:13], off offset:448
	s_add_u32 s2, s2, 0x400
	s_addc_u32 s3, s3, 0
	s_cmpk_eq_i32 s2, 0x800
	s_waitcnt vmcnt(30)
	v_mfma_f32_16x16x32_bf16 v[4:7], v[16:19], v[84:87], v[4:7]
	s_waitcnt vmcnt(28)
	v_mfma_f32_16x16x32_bf16 v[4:7], v[20:23], v[88:91], v[4:7]
	s_waitcnt vmcnt(26)
	v_mfma_f32_16x16x32_bf16 v[4:7], v[24:27], v[92:95], v[4:7]
	s_waitcnt vmcnt(24)
	v_mfma_f32_16x16x32_bf16 v[4:7], v[28:31], v[96:99], v[4:7]
	s_waitcnt vmcnt(22)
	v_mfma_f32_16x16x32_bf16 v[4:7], v[32:35], v[100:103], v[4:7]
	s_waitcnt vmcnt(20)
	v_mfma_f32_16x16x32_bf16 v[4:7], v[36:39], v[104:107], v[4:7]
	s_waitcnt vmcnt(18)
	v_mfma_f32_16x16x32_bf16 v[4:7], v[40:43], v[108:111], v[4:7]
	s_waitcnt vmcnt(16)
	v_mfma_f32_16x16x32_bf16 v[4:7], v[44:47], v[112:115], v[4:7]
	s_waitcnt vmcnt(14)
	v_mfma_f32_16x16x32_bf16 v[4:7], v[48:51], v[116:119], v[4:7]
	s_waitcnt vmcnt(12)
	v_mfma_f32_16x16x32_bf16 v[4:7], v[52:55], v[120:123], v[4:7]
	s_waitcnt vmcnt(10)
	v_mfma_f32_16x16x32_bf16 v[4:7], v[56:59], v[124:127], v[4:7]
	s_waitcnt vmcnt(8)
	v_mfma_f32_16x16x32_bf16 v[4:7], v[60:63], v[140:143], v[4:7]
	s_waitcnt vmcnt(6)
	v_mfma_f32_16x16x32_bf16 v[4:7], v[68:71], v[144:147], v[4:7]
	s_waitcnt vmcnt(4)
	v_mfma_f32_16x16x32_bf16 v[4:7], v[72:75], v[148:151], v[4:7]
	s_waitcnt vmcnt(2)
	v_mfma_f32_16x16x32_bf16 v[4:7], v[76:79], v[152:155], v[4:7]
	s_waitcnt vmcnt(0)
	v_mfma_f32_16x16x32_bf16 v[4:7], v[80:83], v[160:163], v[4:7]
	s_cbranch_scc0 .LBB0_754
	s_and_b32 s16, s93, 63
	v_lshrrev_b32_e32 v106, 4, v159
	v_or_b32_e32 v0, s10, v14
	s_lshl_b32 s2, s16, 7
	v_ashrrev_i32_e32 v1, 31, v0
	v_lshlrev_b32_e32 v8, 2, v106
	s_or_b32 s17, s2, s8
	v_lshl_add_u64 v[0:1], v[0:1], 2, s[82:83]
	v_or_b32_e32 v12, s6, v8
	global_load_dword v9, v[0:1], off
	v_add_u32_e32 v0, s17, v12
	v_ashrrev_i32_e32 v1, 31, v0
	v_readlane_b32 s2, v255, 11
	v_lshlrev_b64 v[10:11], 6, v[0:1]
	v_readlane_b32 s3, v255, 12
	s_nop 1
	v_lshl_add_u64 v[0:1], s[2:3], 0, v[10:11]
	global_load_dwordx4 v[16:19], v[0:1], off offset:16
	global_load_dwordx4 v[20:23], v[0:1], off offset:48
	global_load_dwordx4 v[24:27], v[0:1], off
	global_load_dwordx4 v[28:31], v[0:1], off offset:32
	s_mov_b32 s2, 0x41700000
	s_waitcnt vmcnt(1)
	v_mov_b32_e32 v0, v24
	s_waitcnt vmcnt(0)
	v_mov_b32_e32 v1, v28
	v_mov_b32_e32 v28, v25
	v_mov_b32_e32 v24, v26
	v_mov_b32_e32 v25, v30
	v_mov_b32_e32 v30, v27
	v_pk_add_f32 v[0:1], v[0:1], v[28:29]
	v_pk_add_f32 v[24:25], v[24:25], v[30:31]
	s_nop 0
	v_pk_add_f32 v[0:1], v[0:1], v[24:25]
	v_mov_b32_e32 v24, v16
	v_mov_b32_e32 v25, v20
	v_mov_b32_e32 v20, v17
	v_pk_add_f32 v[16:17], v[24:25], v[20:21]
	v_mov_b32_e32 v20, v18
	v_mov_b32_e32 v21, v22
	v_mov_b32_e32 v22, v19
	v_pk_add_f32 v[18:19], v[20:21], v[22:23]
	s_nop 0
	v_pk_add_f32 v[16:17], v[16:17], v[18:19]
	s_nop 0
	v_pk_add_f32 v[0:1], v[0:1], v[16:17]
	s_nop 0
	v_add_f32_e32 v0, v0, v1
	v_fmamk_f32 v0, v0, 0x3a800000, v191
	v_cmp_gt_f32_e32 vcc, s71, v0
	v_mul_f32_e32 v1, 0x4b800000, v0
	s_nop 0
	v_cndmask_b32_e32 v0, v0, v1, vcc
	v_rsq_f32_e32 v0, v0
	s_nop 0
	v_mul_f32_e32 v1, 0x45800000, v0
	v_cndmask_b32_e32 v0, v0, v1, vcc
	v_fma_f32 v4, v4, v0, v9
	v_cmp_nlt_f32_e32 vcc, s2, v4
	s_and_saveexec_b64 s[2:3], vcc
	s_cbranch_execz .LBB0_757
	v_mul_f32_e32 v0, 0x3fb8aa3b, v4
	v_exp_f32_e32 v2, v0
	s_mov_b32 s8, 0x3f2aaaab
	v_add_f32_e32 v4, 1.0, v2
	v_frexp_mant_f32_e32 v15, v4
	v_cvt_f64_f32_e32 v[0:1], v4
	v_frexp_exp_i32_f64_e32 v0, v[0:1]
	v_cmp_gt_f32_e32 vcc, s8, v15
	v_add_f32_e32 v13, -1.0, v4
	v_sub_f32_e32 v16, v13, v4
	v_subbrev_co_u32_e32 v15, vcc, 0, v0, vcc
	v_sub_u32_e32 v0, 0, v15
	v_sub_f32_e32 v13, v2, v13
	v_add_f32_e32 v16, 1.0, v16
	v_ldexp_f32 v1, v4, v0
	v_add_f32_e32 v13, v13, v16
	v_add_f32_e32 v4, -1.0, v1
	v_add_f32_e32 v16, 1.0, v1
	v_ldexp_f32 v0, v13, v0
	v_add_f32_e32 v13, 1.0, v4
	v_add_f32_e32 v17, -1.0, v16
	v_sub_f32_e32 v13, v1, v13
	v_sub_f32_e32 v1, v1, v17
	v_add_f32_e32 v13, v0, v13
	v_add_f32_e32 v0, v0, v1
	v_add_f32_e32 v22, v16, v0
	v_rcp_f32_e32 v24, v22
	v_sub_f32_e32 v1, v22, v16
	v_sub_f32_e32 v23, v0, v1
	v_add_f32_e32 v1, v4, v13
	v_sub_f32_e32 v0, v1, v4
	v_sub_f32_e32 v4, v13, v0
	v_mul_f32_e32 v13, v1, v24
	v_mul_f32_e32 v16, v22, v13
	v_fma_f32 v18, v13, v22, -v16
	v_fmac_f32_e32 v18, v13, v23
	v_add_f32_e32 v0, v16, v18
	v_sub_f32_e32 v17, v1, v0
	v_pk_add_f32 v[20:21], v[0:1], v[16:17] neg_lo:[0,1] neg_hi:[0,1]
	v_mov_b32_e32 v19, v0
	v_pk_add_f32 v[0:1], v[20:21], v[18:19] neg_lo:[0,1] neg_hi:[0,1]
	s_mov_b32 s8, 0x3f317218
	v_add_f32_e32 v1, v4, v1
	v_add_f32_e32 v0, v0, v1
	v_add_f32_e32 v1, v17, v0
	v_mul_f32_e32 v4, v24, v1
	v_mul_f32_e32 v16, v22, v4
	v_fma_f32 v18, v4, v22, -v16
	v_fmac_f32_e32 v18, v4, v23
	v_sub_f32_e32 v17, v17, v1
	v_add_f32_e32 v22, v0, v17
	v_add_f32_e32 v0, v16, v18
	v_sub_f32_e32 v17, v1, v0
	v_pk_add_f32 v[20:21], v[0:1], v[16:17] neg_lo:[0,1] neg_hi:[0,1]
	v_mov_b32_e32 v19, v0
	v_pk_add_f32 v[0:1], v[20:21], v[18:19] neg_lo:[0,1] neg_hi:[0,1]
	s_nop 0
	v_add_f32_e32 v1, v22, v1
	v_add_f32_e32 v0, v0, v1
	v_add_f32_e32 v1, v13, v4
	v_add_f32_e32 v0, v17, v0
	v_sub_f32_e32 v13, v1, v13
	v_mul_f32_e32 v0, v24, v0
	v_sub_f32_e32 v4, v4, v13
	v_add_f32_e32 v4, v4, v0
	v_add_f32_e32 v13, v1, v4
	v_mul_f32_e32 v16, v13, v13
	v_fmamk_f32 v0, v16, 0x3e9b6dac, v195
	v_fmaak_f32 v137, v16, v0, 0x3f2aaada
	v_cvt_f32_i32_e32 v0, v15
	v_sub_f32_e32 v1, v13, v1
	v_sub_f32_e32 v1, v4, v1
	v_ldexp_f32 v4, v1, 1
	v_mul_f32_e32 v1, v13, v16
	v_pk_mul_f32 v[18:19], v[0:1], v[136:137]
	v_ldexp_f32 v17, v13, 1
	v_fma_f32 v16, v0, s8, -v18
	v_fmac_f32_e32 v16, 0xb102e308, v0
	v_pk_add_f32 v[0:1], v[18:19], v[16:17]
	v_mov_b32_e32 v20, v18
	v_sub_f32_e32 v13, v1, v17
	v_sub_f32_e32 v13, v19, v13
	v_add_f32_e32 v21, v4, v13
	v_pk_add_f32 v[18:19], v[0:1], v[18:19] neg_lo:[0,1] neg_hi:[0,1]
	v_pk_add_f32 v[22:23], v[0:1], v[20:21]
	v_mov_b32_e32 v17, v0
	v_mov_b32_e32 v19, v23
	v_pk_add_f32 v[24:25], v[16:17], v[18:19] neg_lo:[0,1] neg_hi:[0,1]
	v_pk_add_f32 v[16:17], v[16:17], v[18:19]
	v_mov_b32_e32 v20, v21
	v_pk_add_f32 v[18:19], v[16:17], v[0:1] op_sel:[1,0] op_sel_hi:[0,1] neg_lo:[0,1] neg_hi:[0,1]
	v_pk_add_f32 v[26:27], v[22:23], v[18:19] op_sel_hi:[1,0] neg_lo:[0,1] neg_hi:[0,1]
	v_mov_b32_e32 v22, v23
	v_mov_b32_e32 v23, v17
	v_pk_mov_b32 v[18:19], v[0:1], v[18:19] op_sel:[1,0]
	v_mov_b32_e32 v21, v0
	v_pk_add_f32 v[18:19], v[22:23], v[18:19] neg_lo:[0,1] neg_hi:[0,1]
	v_mov_b32_e32 v26, v24
	v_pk_add_f32 v[0:1], v[20:21], v[18:19] neg_lo:[0,1] neg_hi:[0,1]
	v_mov_b32_e32 v25, v17
	v_pk_add_f32 v[18:19], v[26:27], v[0:1]
	s_mov_b32 s8, 0x7f800000
	v_pk_add_f32 v[20:21], v[18:19], v[18:19] op_sel:[0,1] op_sel_hi:[1,0]
	v_cmp_neq_f32_e32 vcc, s8, v2
	v_pk_add_f32 v[16:17], v[16:17], v[20:21] op_sel:[1,0] op_sel_hi:[0,1]
	v_mov_b32_e32 v19, v16
	v_pk_add_f32 v[22:23], v[18:19], v[24:25] neg_lo:[0,1] neg_hi:[0,1]
	v_mov_b32_e32 v1, v20
	v_sub_f32_e32 v4, v18, v22
	v_pk_add_f32 v[0:1], v[0:1], v[22:23] neg_lo:[0,1] neg_hi:[0,1]
	v_sub_f32_e32 v4, v24, v4
	v_add_f32_e32 v0, v0, v4
	v_add_f32_e32 v0, v0, v1
	v_add_f32_e32 v0, v16, v0
	v_cndmask_b32_e32 v0, v203, v0, vcc
	v_cmp_ngt_f32_e32 vcc, -1.0, v2
	s_mov_b32 s8, 0x33800000
	s_nop 0
	v_cndmask_b32_e32 v0, v205, v0, vcc
	v_cmp_neq_f32_e32 vcc, -1.0, v2
	s_nop 1
	v_cndmask_b32_e32 v0, v204, v0, vcc
	v_cmp_lt_f32_e64 vcc, |v2|, s8
	s_nop 1
	v_cndmask_b32_e32 v4, v0, v2, vcc
